# exchange slot reads issued in parallel (6 sites); gMLP row sum-of-squares: all 32 loads in flight instead of load-wait chain
# speedup vs baseline: 1.0070x; 1.0001x over previous
;   DI void exchange(LAS float* part, LAS float* rs, float* slot, unsigned* c, int pm, int pn, int tid) const {
;     ...
;     if (tid < 256) { const unsigned long long* sp8 = (const unsigned long long*)(slot + (size_t)(pm * 256 + tid) * 8); float tot = 0.f;
; #pragma unroll
;       for (int k = 0; k < 4; ++k) { const unsigned long long q = __hip_atomic_load(sp8 + k, __ATOMIC_RELAXED, __HIP_MEMORY_SCOPE_AGENT);
;         tot += __uint_as_float((unsigned)q) + __uint_as_float((unsigned)(q >> 32)); }
;       rs[tid] = rsqrtf(tot * (1.0f / 2048.0f) + EPS); }
.LBB0_299:
	s_or_b64 exec, exec, s[0:1]
	s_barrier
	s_and_saveexec_b64 s[0:1], s[36:37]
	s_cbranch_execz .LBB0_301
	v_add_u32_e32 v144, s12, v208
	v_ashrrev_i32_e32 v145, 31, v144
	v_readlane_b32 s22, v255, 1
	v_lshlrev_b64 v[144:145], 5, v[144:145]
	v_readlane_b32 s23, v255, 2
	s_nop 1
	v_lshl_add_u64 v[144:145], s[22:23], 0, v[144:145]
	global_load_dwordx2 v[146:147], v[144:145], off sc1
	global_load_dwordx2 v[150:151], v[144:145], off offset:8 sc1
	global_load_dwordx2 v[152:153], v[144:145], off offset:16 sc1
	global_load_dwordx2 v[144:145], v[144:145], off offset:24 sc1
	s_waitcnt vmcnt(0)
	v_add_f32_e32 v146, v146, v147
	v_add_f32_e32 v146, 0, v146
	v_add_f32_e32 v150, v150, v151
	v_add_f32_e32 v146, v146, v150
	v_add_f32_e32 v152, v152, v153
	v_add_f32_e32 v146, v146, v152
	v_add_f32_e32 v144, v144, v145
	v_add_f32_e32 v144, v146, v144
	v_fmamk_f32 v144, v144, 0x3a000000, v235
	v_cmp_gt_f32_e32 vcc, s95, v144
	v_mul_f32_e32 v145, 0x4b800000, v144
	s_nop 0
	v_cndmask_b32_e32 v144, v144, v145, vcc
	v_rsq_f32_e32 v144, v144
	s_nop 0
	v_mul_f32_e32 v145, 0x45800000, v144
	v_cndmask_b32_e32 v144, v144, v145, vcc
	v_lshl_add_u32 v145, v208, 2, 0
	ds_write_b32 v145, v144 offset:4096

;   DI void exchange(LAS float* part, LAS float* rs, float* slot, unsigned* c, int pm, int pn, int tid) const {
;     ...
;     if (tid < 256) { const unsigned long long* sp8 = (const unsigned long long*)(slot + (size_t)(pm * 256 + tid) * 8); float tot = 0.f;
; #pragma unroll
;       for (int k = 0; k < 4; ++k) { const unsigned long long q = __hip_atomic_load(sp8 + k, __ATOMIC_RELAXED, __HIP_MEMORY_SCOPE_AGENT);
;         tot += __uint_as_float((unsigned)q) + __uint_as_float((unsigned)(q >> 32)); }
;       rs[tid] = rsqrtf(tot * (1.0f / 2048.0f) + EPS); }
.LBB0_414:
	s_or_b64 exec, exec, s[0:1]
	s_barrier
	s_and_saveexec_b64 s[0:1], s[36:37]
	s_cbranch_execz .LBB0_416
	v_readlane_b32 s22, v255, 3
	v_lshlrev_b64 v[4:5], 5, v[0:1]
	v_readlane_b32 s23, v255, 4
	s_nop 1
	v_lshl_add_u64 v[4:5], s[22:23], 0, v[4:5]
	global_load_dwordx2 v[6:7], v[4:5], off sc1
	global_load_dwordx2 v[8:9], v[4:5], off offset:8 sc1
	global_load_dwordx2 v[10:11], v[4:5], off offset:16 sc1
	global_load_dwordx2 v[4:5], v[4:5], off offset:24 sc1
	s_waitcnt vmcnt(0)
	v_add_f32_e32 v6, v6, v7
	v_add_f32_e32 v6, 0, v6
	v_add_f32_e32 v8, v8, v9
	v_add_f32_e32 v6, v6, v8
	v_add_f32_e32 v10, v10, v11
	v_add_f32_e32 v6, v6, v10
	v_add_f32_e32 v4, v4, v5
	v_add_f32_e32 v3, v6, v4
	v_fmamk_f32 v3, v3, 0x3a000000, v235
	v_cmp_gt_f32_e32 vcc, s95, v3
	v_mul_f32_e32 v4, 0x4b800000, v3
	s_nop 0
	v_cndmask_b32_e32 v3, v3, v4, vcc
	v_rsq_f32_e32 v3, v3
	s_nop 0
	v_mul_f32_e32 v4, 0x45800000, v3
	v_cndmask_b32_e32 v3, v3, v4, vcc
	ds_write_b32 v2, v3 offset:4096

;   DI void exchange(LAS float* part, LAS float* rs, float* slot, unsigned* c, int pm, int pn, int tid) const {
;     ...
;     if (tid < 256) { const unsigned long long* sp8 = (const unsigned long long*)(slot + (size_t)(pm * 256 + tid) * 8); float tot = 0.f;
; #pragma unroll
;       for (int k = 0; k < 4; ++k) { const unsigned long long q = __hip_atomic_load(sp8 + k, __ATOMIC_RELAXED, __HIP_MEMORY_SCOPE_AGENT);
;         tot += __uint_as_float((unsigned)q) + __uint_as_float((unsigned)(q >> 32)); }
;       rs[tid] = rsqrtf(tot * (1.0f / 2048.0f) + EPS); }
.LBB0_582:
	s_or_b64 exec, exec, s[22:23]
	s_barrier
	s_and_saveexec_b64 s[22:23], s[38:39]
	s_cbranch_execz .LBB0_584
	v_readlane_b32 s24, v255, 1
	v_lshlrev_b64 v[148:149], 5, v[220:221]
	v_readlane_b32 s25, v255, 2
	s_nop 1
	v_lshl_add_u64 v[148:149], s[24:25], 0, v[148:149]
	global_load_dwordx2 v[150:151], v[148:149], off sc1
	global_load_dwordx2 v[152:153], v[148:149], off offset:8 sc1
	global_load_dwordx2 v[154:155], v[148:149], off offset:16 sc1
	global_load_dwordx2 v[148:149], v[148:149], off offset:24 sc1
	s_waitcnt vmcnt(0)
	v_add_f32_e32 v150, v150, v151
	v_add_f32_e32 v150, 0, v150
	v_add_f32_e32 v152, v152, v153
	v_add_f32_e32 v150, v150, v152
	v_add_f32_e32 v154, v154, v155
	v_add_f32_e32 v150, v150, v154
	v_add_f32_e32 v148, v148, v149
	v_add_f32_e32 v147, v150, v148
	v_fmamk_f32 v147, v147, 0x3a000000, v235
	v_cmp_gt_f32_e32 vcc, s95, v147
	v_mul_f32_e32 v148, 0x4b800000, v147
	s_nop 0
	v_cndmask_b32_e32 v147, v147, v148, vcc
	v_rsq_f32_e32 v147, v147
	s_nop 0
	v_mul_f32_e32 v148, 0x45800000, v147
	v_cndmask_b32_e32 v147, v147, v148, vcc
	ds_write_b32 v239, v147 offset:4096

;   DI void exchange(LAS float* part, LAS float* rs, float* slot, unsigned* c, int pm, int pn, int tid) const {
;     ...
;     if (tid < 256) { const unsigned long long* sp8 = (const unsigned long long*)(slot + (size_t)(pm * 256 + tid) * 8); float tot = 0.f;
; #pragma unroll
;       for (int k = 0; k < 4; ++k) { const unsigned long long q = __hip_atomic_load(sp8 + k, __ATOMIC_RELAXED, __HIP_MEMORY_SCOPE_AGENT);
;         tot += __uint_as_float((unsigned)q) + __uint_as_float((unsigned)(q >> 32)); }
;       rs[tid] = rsqrtf(tot * (1.0f / 2048.0f) + EPS); }
.LBB0_618:
	s_or_b64 exec, exec, s[22:23]
	s_barrier
	s_and_saveexec_b64 s[22:23], s[38:39]
	s_cbranch_execz .LBB0_620
	v_readlane_b32 s24, v255, 3
	v_lshlrev_b64 v[0:1], 5, v[220:221]
	v_readlane_b32 s25, v255, 4
	s_nop 1
	v_lshl_add_u64 v[0:1], s[24:25], 0, v[0:1]
	global_load_dwordx2 v[2:3], v[0:1], off sc1
	global_load_dwordx2 v[6:7], v[0:1], off offset:8 sc1
	global_load_dwordx2 v[8:9], v[0:1], off offset:16 sc1
	global_load_dwordx2 v[0:1], v[0:1], off offset:24 sc1
	s_waitcnt vmcnt(0)
	v_add_f32_e32 v2, v2, v3
	v_add_f32_e32 v2, 0, v2
	v_add_f32_e32 v6, v6, v7
	v_add_f32_e32 v2, v2, v6
	v_add_f32_e32 v8, v8, v9
	v_add_f32_e32 v2, v2, v8
	v_add_f32_e32 v0, v0, v1
	v_add_f32_e32 v0, v2, v0
	v_fmamk_f32 v0, v0, 0x3a000000, v235
	v_cmp_gt_f32_e32 vcc, s95, v0
	v_mul_f32_e32 v1, 0x4b800000, v0
	s_nop 0
	v_cndmask_b32_e32 v0, v0, v1, vcc
	v_rsq_f32_e32 v0, v0
	s_nop 0
	v_mul_f32_e32 v1, 0x45800000, v0
	v_cndmask_b32_e32 v0, v0, v1, vcc
	ds_write_b32 v239, v0 offset:4096

;   DI void exchange(LAS float* part, LAS float* rs, float* slot, unsigned* c, int pm, int pn, int tid) const {
;     ...
;     if (tid < 256) { const unsigned long long* sp8 = (const unsigned long long*)(slot + (size_t)(pm * 256 + tid) * 8); float tot = 0.f;
; #pragma unroll
;       for (int k = 0; k < 4; ++k) { const unsigned long long q = __hip_atomic_load(sp8 + k, __ATOMIC_RELAXED, __HIP_MEMORY_SCOPE_AGENT);
;         tot += __uint_as_float((unsigned)q) + __uint_as_float((unsigned)(q >> 32)); }
;       rs[tid] = rsqrtf(tot * (1.0f / 2048.0f) + EPS); }
.LBB0_682:
	s_or_b64 exec, exec, s[22:23]
	s_lshl_b32 s1, s40, 8
	v_add_u32_e32 v144, s1, v151
	v_ashrrev_i32_e32 v145, 31, v144
	s_barrier
	s_and_saveexec_b64 s[22:23], s[34:35]
	s_cbranch_execz .LBB0_684
	v_readlane_b32 s10, v255, 1
	v_lshlrev_b64 v[148:149], 5, v[144:145]
	v_readlane_b32 s11, v255, 2
	s_nop 1
	v_lshl_add_u64 v[148:149], s[10:11], 0, v[148:149]
	global_load_dwordx2 v[158:159], v[148:149], off sc1
	global_load_dwordx2 v[160:161], v[148:149], off offset:8 sc1
	global_load_dwordx2 v[162:163], v[148:149], off offset:16 sc1
	global_load_dwordx2 v[148:149], v[148:149], off offset:24 sc1
	s_waitcnt vmcnt(0)
	v_add_f32_e32 v158, v158, v159
	v_add_f32_e32 v158, 0, v158
	v_add_f32_e32 v160, v160, v161
	v_add_f32_e32 v158, v158, v160
	v_add_f32_e32 v162, v162, v163
	v_add_f32_e32 v158, v158, v162
	v_add_f32_e32 v148, v148, v149
	v_add_f32_e32 v148, v158, v148
	v_fmamk_f32 v148, v148, 0x3a000000, v235
	v_cmp_gt_f32_e32 vcc, s95, v148
	v_mul_f32_e32 v149, 0x4b800000, v148
	s_nop 0
	v_cndmask_b32_e32 v148, v148, v149, vcc
	v_rsq_f32_e32 v148, v148
	s_nop 0
	v_mul_f32_e32 v149, 0x45800000, v148
	v_cndmask_b32_e32 v148, v148, v149, vcc
	ds_write_b32 v152, v148 offset:4096

;   DI void exchange(LAS float* part, LAS float* rs, float* slot, unsigned* c, int pm, int pn, int tid) const {
;     ...
;     if (tid < 256) { const unsigned long long* sp8 = (const unsigned long long*)(slot + (size_t)(pm * 256 + tid) * 8); float tot = 0.f;
; #pragma unroll
;       for (int k = 0; k < 4; ++k) { const unsigned long long q = __hip_atomic_load(sp8 + k, __ATOMIC_RELAXED, __HIP_MEMORY_SCOPE_AGENT);
;         tot += __uint_as_float((unsigned)q) + __uint_as_float((unsigned)(q >> 32)); }
;       rs[tid] = rsqrtf(tot * (1.0f / 2048.0f) + EPS); }
.LBB0_718:
	s_or_b64 exec, exec, s[22:23]
	s_barrier
	s_and_saveexec_b64 s[22:23], s[34:35]
	s_cbranch_execz .LBB0_720
	v_readlane_b32 s10, v255, 3
	v_lshlrev_b64 v[0:1], 5, v[144:145]
	v_readlane_b32 s11, v255, 4
	s_nop 1
	v_lshl_add_u64 v[0:1], s[10:11], 0, v[0:1]
	global_load_dwordx2 v[2:3], v[0:1], off sc1
	global_load_dwordx2 v[6:7], v[0:1], off offset:8 sc1
	global_load_dwordx2 v[8:9], v[0:1], off offset:16 sc1
	global_load_dwordx2 v[0:1], v[0:1], off offset:24 sc1
	s_waitcnt vmcnt(0)
	v_add_f32_e32 v2, v2, v3
	v_add_f32_e32 v2, 0, v2
	v_add_f32_e32 v6, v6, v7
	v_add_f32_e32 v2, v2, v6
	v_add_f32_e32 v8, v8, v9
	v_add_f32_e32 v2, v2, v8
	v_add_f32_e32 v0, v0, v1
	v_add_f32_e32 v0, v2, v0
	v_fmamk_f32 v0, v0, 0x3a000000, v235
	v_cmp_gt_f32_e32 vcc, s95, v0
	v_mul_f32_e32 v1, 0x4b800000, v0
	s_nop 0
	v_cndmask_b32_e32 v0, v0, v1, vcc
	v_rsq_f32_e32 v0, v0
	s_nop 0
	v_mul_f32_e32 v1, 0x45800000, v0
	v_cndmask_b32_e32 v0, v0, v1, vcc
	ds_write_b32 v152, v0 offset:4096

; DI float bf_lo(unsigned w) { return __uint_as_float(w << 16); }
; DI float bf_hi(unsigned w) { return __uint_as_float(w & 0xffff0000u); }
; DI void gm_unit(const Ctx& cx, const bf16_t* __restrict__ PG, bf16_t* __restrict__ Ogm, const float* __restrict__ gvn, const float* __restrict__ ws, const float* __restrict__ bs, int unit, LAS unsigned char* lds) {
;     ...
;   { const int tt = tid >> 2, part = tid & 3; const bf16_t* vp = PG + (size_t)(tok0 + tt) * PGW + 4096; float ss = 0.f;
; #pragma unroll 8
;     for (int i = 0; i < 32; ++i) { const u32x4 w = *(const u32x4*)(vp + (i * 4 + part) * 8);
;       float g;
;       g = bf_lo(w.x); ss += g * g; g = bf_hi(w.x); ss += g * g; g = bf_lo(w.y); ss += g * g; g = bf_hi(w.y); ss += g * g;
;       g = bf_lo(w.z); ss += g * g; g = bf_hi(w.z); ss += g * g; g = bf_lo(w.w); ss += g * g; g = bf_hi(w.w); ss += g * g; }
;     ss += __shfl_xor(ss, 1); ss += __shfl_xor(ss, 2);
;     if (part == 0) rinv[tt] = rsqrtf(ss * (1.0f / 1024.0f) + EPS); }
.LBB0_912:
	global_load_dwordx4 v[104:107], v[0:1], off offset:-256
	global_load_dwordx4 v[108:111], v[0:1], off offset:-192
	global_load_dwordx4 v[112:115], v[0:1], off offset:-128
	global_load_dwordx4 v[116:119], v[0:1], off offset:-64
	global_load_dwordx4 v[120:123], v[0:1], off
	global_load_dwordx4 v[124:127], v[0:1], off offset:64
	global_load_dwordx4 v[128:131], v[0:1], off offset:128
	global_load_dwordx4 v[132:135], v[0:1], off offset:192
	global_load_dwordx4 v[64:67], v[0:1], off offset:256
	global_load_dwordx4 v[68:71], v[0:1], off offset:320
	global_load_dwordx4 v[72:75], v[0:1], off offset:384
	global_load_dwordx4 v[76:79], v[0:1], off offset:448
	global_load_dwordx4 v[80:83], v[0:1], off offset:512
	global_load_dwordx4 v[84:87], v[0:1], off offset:576
	global_load_dwordx4 v[4:7], v[0:1], off offset:640
	global_load_dwordx4 v[8:11], v[0:1], off offset:704
	global_load_dwordx4 v[12:15], v[0:1], off offset:768
	global_load_dwordx4 v[16:19], v[0:1], off offset:832
	global_load_dwordx4 v[20:23], v[0:1], off offset:896
	global_load_dwordx4 v[24:27], v[0:1], off offset:960
	global_load_dwordx4 v[28:31], v[0:1], off offset:1024
	global_load_dwordx4 v[146:149], v[0:1], off offset:1088
	global_load_dwordx4 v[150:153], v[0:1], off offset:1152
	global_load_dwordx4 v[154:157], v[0:1], off offset:1216
	global_load_dwordx4 v[158:161], v[0:1], off offset:1280
	global_load_dwordx4 v[162:165], v[0:1], off offset:1344
	global_load_dwordx4 v[180:183], v[0:1], off offset:1408
	global_load_dwordx4 v[184:187], v[0:1], off offset:1472
	global_load_dwordx4 v[188:191], v[0:1], off offset:1536
	global_load_dwordx4 v[192:195], v[0:1], off offset:1600
	global_load_dwordx4 v[196:199], v[0:1], off offset:1664
	global_load_dwordx4 v[200:203], v[0:1], off offset:1728
	s_waitcnt vmcnt(31)
	v_lshlrev_b32_e32 v3, 16, v104
	v_fmac_f32_e32 v2, v3, v3
	v_and_b32_e32 v3, 0xffff0000, v104
	v_fmac_f32_e32 v2, v3, v3
	v_lshlrev_b32_e32 v3, 16, v105
	v_fmac_f32_e32 v2, v3, v3
	v_and_b32_e32 v3, 0xffff0000, v105
	v_fmac_f32_e32 v2, v3, v3
	v_lshlrev_b32_e32 v3, 16, v106
	v_fmac_f32_e32 v2, v3, v3
	v_and_b32_e32 v3, 0xffff0000, v106
	v_fmac_f32_e32 v2, v3, v3
	v_lshlrev_b32_e32 v3, 16, v107
	v_fmac_f32_e32 v2, v3, v3
	v_and_b32_e32 v3, 0xffff0000, v107
	v_fmac_f32_e32 v2, v3, v3
	s_waitcnt vmcnt(30)
	v_lshlrev_b32_e32 v3, 16, v108
	v_fmac_f32_e32 v2, v3, v3
	v_and_b32_e32 v3, 0xffff0000, v108
	v_fmac_f32_e32 v2, v3, v3
	v_lshlrev_b32_e32 v3, 16, v109
	v_fmac_f32_e32 v2, v3, v3
	v_and_b32_e32 v3, 0xffff0000, v109
	v_fmac_f32_e32 v2, v3, v3
	v_lshlrev_b32_e32 v3, 16, v110
	v_fmac_f32_e32 v2, v3, v3
	v_and_b32_e32 v3, 0xffff0000, v110
	v_fmac_f32_e32 v2, v3, v3
	v_lshlrev_b32_e32 v3, 16, v111
	v_fmac_f32_e32 v2, v3, v3
	v_and_b32_e32 v3, 0xffff0000, v111
	v_fmac_f32_e32 v2, v3, v3
	s_waitcnt vmcnt(29)
	v_lshlrev_b32_e32 v3, 16, v112
	v_fmac_f32_e32 v2, v3, v3
	v_and_b32_e32 v3, 0xffff0000, v112
	v_fmac_f32_e32 v2, v3, v3
	v_lshlrev_b32_e32 v3, 16, v113
	v_fmac_f32_e32 v2, v3, v3
	v_and_b32_e32 v3, 0xffff0000, v113
	v_fmac_f32_e32 v2, v3, v3
	v_lshlrev_b32_e32 v3, 16, v114
	v_fmac_f32_e32 v2, v3, v3
	v_and_b32_e32 v3, 0xffff0000, v114
	v_fmac_f32_e32 v2, v3, v3
	v_lshlrev_b32_e32 v3, 16, v115
	v_fmac_f32_e32 v2, v3, v3
	v_and_b32_e32 v3, 0xffff0000, v115
	v_fmac_f32_e32 v2, v3, v3
	s_waitcnt vmcnt(28)
	v_lshlrev_b32_e32 v3, 16, v116
	v_fmac_f32_e32 v2, v3, v3
	v_and_b32_e32 v3, 0xffff0000, v116
	v_fmac_f32_e32 v2, v3, v3
	v_lshlrev_b32_e32 v3, 16, v117
	v_fmac_f32_e32 v2, v3, v3
	v_and_b32_e32 v3, 0xffff0000, v117
	v_fmac_f32_e32 v2, v3, v3
	v_lshlrev_b32_e32 v3, 16, v118
	v_fmac_f32_e32 v2, v3, v3
	v_and_b32_e32 v3, 0xffff0000, v118
	v_fmac_f32_e32 v2, v3, v3
	v_lshlrev_b32_e32 v3, 16, v119
	v_fmac_f32_e32 v2, v3, v3
	v_and_b32_e32 v3, 0xffff0000, v119
	v_fmac_f32_e32 v2, v3, v3
	s_waitcnt vmcnt(27)
	v_lshlrev_b32_e32 v3, 16, v120
	v_fmac_f32_e32 v2, v3, v3
	v_and_b32_e32 v3, 0xffff0000, v120
	v_fmac_f32_e32 v2, v3, v3
	v_lshlrev_b32_e32 v3, 16, v121
	v_fmac_f32_e32 v2, v3, v3
	v_and_b32_e32 v3, 0xffff0000, v121
	v_fmac_f32_e32 v2, v3, v3
	v_lshlrev_b32_e32 v3, 16, v122
	v_fmac_f32_e32 v2, v3, v3
	v_and_b32_e32 v3, 0xffff0000, v122
	v_fmac_f32_e32 v2, v3, v3
	v_lshlrev_b32_e32 v3, 16, v123
	v_fmac_f32_e32 v2, v3, v3
	v_and_b32_e32 v3, 0xffff0000, v123
	v_fmac_f32_e32 v2, v3, v3
	s_waitcnt vmcnt(26)
	v_lshlrev_b32_e32 v3, 16, v124
	v_fmac_f32_e32 v2, v3, v3
	v_and_b32_e32 v3, 0xffff0000, v124
	v_fmac_f32_e32 v2, v3, v3
	v_lshlrev_b32_e32 v3, 16, v125
	v_fmac_f32_e32 v2, v3, v3
	v_and_b32_e32 v3, 0xffff0000, v125
	v_fmac_f32_e32 v2, v3, v3
	v_lshlrev_b32_e32 v3, 16, v126
	v_fmac_f32_e32 v2, v3, v3
	v_and_b32_e32 v3, 0xffff0000, v126
	v_fmac_f32_e32 v2, v3, v3
	v_lshlrev_b32_e32 v3, 16, v127
	v_fmac_f32_e32 v2, v3, v3
	v_and_b32_e32 v3, 0xffff0000, v127
	v_fmac_f32_e32 v2, v3, v3
	s_waitcnt vmcnt(25)
	v_lshlrev_b32_e32 v3, 16, v128
	v_fmac_f32_e32 v2, v3, v3
	v_and_b32_e32 v3, 0xffff0000, v128
	v_fmac_f32_e32 v2, v3, v3
	v_lshlrev_b32_e32 v3, 16, v129
	v_fmac_f32_e32 v2, v3, v3
	v_and_b32_e32 v3, 0xffff0000, v129
	v_fmac_f32_e32 v2, v3, v3
	v_lshlrev_b32_e32 v3, 16, v130
	v_fmac_f32_e32 v2, v3, v3
	v_and_b32_e32 v3, 0xffff0000, v130
	v_fmac_f32_e32 v2, v3, v3
	v_lshlrev_b32_e32 v3, 16, v131
	v_fmac_f32_e32 v2, v3, v3
	v_and_b32_e32 v3, 0xffff0000, v131
	v_fmac_f32_e32 v2, v3, v3
	s_waitcnt vmcnt(24)
	v_lshlrev_b32_e32 v3, 16, v132
	v_fmac_f32_e32 v2, v3, v3
	v_and_b32_e32 v3, 0xffff0000, v132
	v_fmac_f32_e32 v2, v3, v3
	v_lshlrev_b32_e32 v3, 16, v133
	v_fmac_f32_e32 v2, v3, v3
	v_and_b32_e32 v3, 0xffff0000, v133
	v_fmac_f32_e32 v2, v3, v3
	v_lshlrev_b32_e32 v3, 16, v134
	v_fmac_f32_e32 v2, v3, v3
	v_and_b32_e32 v3, 0xffff0000, v134
	v_fmac_f32_e32 v2, v3, v3
	v_lshlrev_b32_e32 v3, 16, v135
	v_fmac_f32_e32 v2, v3, v3
	v_and_b32_e32 v3, 0xffff0000, v135
	v_fmac_f32_e32 v2, v3, v3
	s_waitcnt vmcnt(23)
; DI float bf_lo(unsigned w) { return __uint_as_float(w << 16); }
; DI float bf_hi(unsigned w) { return __uint_as_float(w & 0xffff0000u); }
; DI void gm_unit(const Ctx& cx, const bf16_t* __restrict__ PG, bf16_t* __restrict__ Ogm, const float* __restrict__ gvn, const float* __restrict__ ws, const float* __restrict__ bs, int unit, LAS unsigned char* lds) {
;     ...
;   { const int tt = tid >> 2, part = tid & 3; const bf16_t* vp = PG + (size_t)(tok0 + tt) * PGW + 4096; float ss = 0.f;
; #pragma unroll 8
;     for (int i = 0; i < 32; ++i) { const u32x4 w = *(const u32x4*)(vp + (i * 4 + part) * 8);
;       float g;
;       g = bf_lo(w.x); ss += g * g; g = bf_hi(w.x); ss += g * g; g = bf_lo(w.y); ss += g * g; g = bf_hi(w.y); ss += g * g;
;       g = bf_lo(w.z); ss += g * g; g = bf_hi(w.z); ss += g * g; g = bf_lo(w.w); ss += g * g; g = bf_hi(w.w); ss += g * g; }
;     ss += __shfl_xor(ss, 1); ss += __shfl_xor(ss, 2);
;     if (part == 0) rinv[tt] = rsqrtf(ss * (1.0f / 1024.0f) + EPS); }
	v_lshlrev_b32_e32 v3, 16, v64
	v_fmac_f32_e32 v2, v3, v3
	v_and_b32_e32 v3, 0xffff0000, v64
	v_fmac_f32_e32 v2, v3, v3
	v_lshlrev_b32_e32 v3, 16, v65
	v_fmac_f32_e32 v2, v3, v3
	v_and_b32_e32 v3, 0xffff0000, v65
	v_fmac_f32_e32 v2, v3, v3
	v_lshlrev_b32_e32 v3, 16, v66
	v_fmac_f32_e32 v2, v3, v3
	v_and_b32_e32 v3, 0xffff0000, v66
	v_fmac_f32_e32 v2, v3, v3
	v_lshlrev_b32_e32 v3, 16, v67
	v_fmac_f32_e32 v2, v3, v3
	v_and_b32_e32 v3, 0xffff0000, v67
	v_fmac_f32_e32 v2, v3, v3
	s_waitcnt vmcnt(22)
	v_lshlrev_b32_e32 v3, 16, v68
	v_fmac_f32_e32 v2, v3, v3
	v_and_b32_e32 v3, 0xffff0000, v68
	v_fmac_f32_e32 v2, v3, v3
	v_lshlrev_b32_e32 v3, 16, v69
	v_fmac_f32_e32 v2, v3, v3
	v_and_b32_e32 v3, 0xffff0000, v69
	v_fmac_f32_e32 v2, v3, v3
	v_lshlrev_b32_e32 v3, 16, v70
	v_fmac_f32_e32 v2, v3, v3
	v_and_b32_e32 v3, 0xffff0000, v70
	v_fmac_f32_e32 v2, v3, v3
	v_lshlrev_b32_e32 v3, 16, v71
	v_fmac_f32_e32 v2, v3, v3
	v_and_b32_e32 v3, 0xffff0000, v71
	v_fmac_f32_e32 v2, v3, v3
	s_waitcnt vmcnt(21)
	v_lshlrev_b32_e32 v3, 16, v72
	v_fmac_f32_e32 v2, v3, v3
	v_and_b32_e32 v3, 0xffff0000, v72
	v_fmac_f32_e32 v2, v3, v3
	v_lshlrev_b32_e32 v3, 16, v73
	v_fmac_f32_e32 v2, v3, v3
	v_and_b32_e32 v3, 0xffff0000, v73
	v_fmac_f32_e32 v2, v3, v3
	v_lshlrev_b32_e32 v3, 16, v74
	v_fmac_f32_e32 v2, v3, v3
	v_and_b32_e32 v3, 0xffff0000, v74
	v_fmac_f32_e32 v2, v3, v3
	v_lshlrev_b32_e32 v3, 16, v75
	v_fmac_f32_e32 v2, v3, v3
	v_and_b32_e32 v3, 0xffff0000, v75
	v_fmac_f32_e32 v2, v3, v3
	s_waitcnt vmcnt(20)
	v_lshlrev_b32_e32 v3, 16, v76
	v_fmac_f32_e32 v2, v3, v3
	v_and_b32_e32 v3, 0xffff0000, v76
	v_fmac_f32_e32 v2, v3, v3
	v_lshlrev_b32_e32 v3, 16, v77
	v_fmac_f32_e32 v2, v3, v3
	v_and_b32_e32 v3, 0xffff0000, v77
	v_fmac_f32_e32 v2, v3, v3
	v_lshlrev_b32_e32 v3, 16, v78
	v_fmac_f32_e32 v2, v3, v3
	v_and_b32_e32 v3, 0xffff0000, v78
	v_fmac_f32_e32 v2, v3, v3
	v_lshlrev_b32_e32 v3, 16, v79
	v_fmac_f32_e32 v2, v3, v3
	v_and_b32_e32 v3, 0xffff0000, v79
	v_fmac_f32_e32 v2, v3, v3
	s_waitcnt vmcnt(19)
	v_lshlrev_b32_e32 v3, 16, v80
	v_fmac_f32_e32 v2, v3, v3
	v_and_b32_e32 v3, 0xffff0000, v80
	v_fmac_f32_e32 v2, v3, v3
	v_lshlrev_b32_e32 v3, 16, v81
	v_fmac_f32_e32 v2, v3, v3
	v_and_b32_e32 v3, 0xffff0000, v81
	v_fmac_f32_e32 v2, v3, v3
	v_lshlrev_b32_e32 v3, 16, v82
	v_fmac_f32_e32 v2, v3, v3
	v_and_b32_e32 v3, 0xffff0000, v82
	v_fmac_f32_e32 v2, v3, v3
	v_lshlrev_b32_e32 v3, 16, v83
	v_fmac_f32_e32 v2, v3, v3
	v_and_b32_e32 v3, 0xffff0000, v83
	v_fmac_f32_e32 v2, v3, v3
	s_waitcnt vmcnt(18)
	v_lshlrev_b32_e32 v3, 16, v84
	v_fmac_f32_e32 v2, v3, v3
	v_and_b32_e32 v3, 0xffff0000, v84
	v_fmac_f32_e32 v2, v3, v3
	v_lshlrev_b32_e32 v3, 16, v85
	v_fmac_f32_e32 v2, v3, v3
	v_and_b32_e32 v3, 0xffff0000, v85
	v_fmac_f32_e32 v2, v3, v3
	v_lshlrev_b32_e32 v3, 16, v86
	v_fmac_f32_e32 v2, v3, v3
	v_and_b32_e32 v3, 0xffff0000, v86
	v_fmac_f32_e32 v2, v3, v3
	v_lshlrev_b32_e32 v3, 16, v87
	v_fmac_f32_e32 v2, v3, v3
	v_and_b32_e32 v3, 0xffff0000, v87
	v_fmac_f32_e32 v2, v3, v3
	s_waitcnt vmcnt(17)
	v_lshlrev_b32_e32 v3, 16, v4
	v_fmac_f32_e32 v2, v3, v3
	v_and_b32_e32 v3, 0xffff0000, v4
	v_fmac_f32_e32 v2, v3, v3
	v_lshlrev_b32_e32 v3, 16, v5
	v_fmac_f32_e32 v2, v3, v3
	v_and_b32_e32 v3, 0xffff0000, v5
	v_fmac_f32_e32 v2, v3, v3
	v_lshlrev_b32_e32 v3, 16, v6
	v_fmac_f32_e32 v2, v3, v3
	v_and_b32_e32 v3, 0xffff0000, v6
	v_fmac_f32_e32 v2, v3, v3
	v_lshlrev_b32_e32 v3, 16, v7
	v_fmac_f32_e32 v2, v3, v3
	v_and_b32_e32 v3, 0xffff0000, v7
	v_fmac_f32_e32 v2, v3, v3
	s_waitcnt vmcnt(16)
	v_lshlrev_b32_e32 v3, 16, v8
	v_fmac_f32_e32 v2, v3, v3
	v_and_b32_e32 v3, 0xffff0000, v8
	v_fmac_f32_e32 v2, v3, v3
	v_lshlrev_b32_e32 v3, 16, v9
	v_fmac_f32_e32 v2, v3, v3
	v_and_b32_e32 v3, 0xffff0000, v9
	v_fmac_f32_e32 v2, v3, v3
	v_lshlrev_b32_e32 v3, 16, v10
	v_fmac_f32_e32 v2, v3, v3
	v_and_b32_e32 v3, 0xffff0000, v10
	v_fmac_f32_e32 v2, v3, v3
	v_lshlrev_b32_e32 v3, 16, v11
	v_fmac_f32_e32 v2, v3, v3
	v_and_b32_e32 v3, 0xffff0000, v11
	v_fmac_f32_e32 v2, v3, v3
	s_waitcnt vmcnt(15)
	v_lshlrev_b32_e32 v3, 16, v12
	v_fmac_f32_e32 v2, v3, v3
	v_and_b32_e32 v3, 0xffff0000, v12
	v_fmac_f32_e32 v2, v3, v3
	v_lshlrev_b32_e32 v3, 16, v13
	v_fmac_f32_e32 v2, v3, v3
	v_and_b32_e32 v3, 0xffff0000, v13
	v_fmac_f32_e32 v2, v3, v3
	v_lshlrev_b32_e32 v3, 16, v14
	v_fmac_f32_e32 v2, v3, v3
	v_and_b32_e32 v3, 0xffff0000, v14
	v_fmac_f32_e32 v2, v3, v3
	v_lshlrev_b32_e32 v3, 16, v15
	v_fmac_f32_e32 v2, v3, v3
	v_and_b32_e32 v3, 0xffff0000, v15
	v_fmac_f32_e32 v2, v3, v3
	s_waitcnt vmcnt(14)
	v_lshlrev_b32_e32 v3, 16, v16
	v_fmac_f32_e32 v2, v3, v3
	v_and_b32_e32 v3, 0xffff0000, v16
	v_fmac_f32_e32 v2, v3, v3
	v_lshlrev_b32_e32 v3, 16, v17
	v_fmac_f32_e32 v2, v3, v3
	v_and_b32_e32 v3, 0xffff0000, v17
	v_fmac_f32_e32 v2, v3, v3
	v_lshlrev_b32_e32 v3, 16, v18
	v_fmac_f32_e32 v2, v3, v3
	v_and_b32_e32 v3, 0xffff0000, v18
	v_fmac_f32_e32 v2, v3, v3
	v_lshlrev_b32_e32 v3, 16, v19
	v_fmac_f32_e32 v2, v3, v3
	v_and_b32_e32 v3, 0xffff0000, v19
	v_fmac_f32_e32 v2, v3, v3
	s_waitcnt vmcnt(13)
	v_lshlrev_b32_e32 v3, 16, v20
	v_fmac_f32_e32 v2, v3, v3
	v_and_b32_e32 v3, 0xffff0000, v20
	v_fmac_f32_e32 v2, v3, v3
	v_lshlrev_b32_e32 v3, 16, v21
	v_fmac_f32_e32 v2, v3, v3
	v_and_b32_e32 v3, 0xffff0000, v21
	v_fmac_f32_e32 v2, v3, v3
	v_lshlrev_b32_e32 v3, 16, v22
	v_fmac_f32_e32 v2, v3, v3
	v_and_b32_e32 v3, 0xffff0000, v22
	v_fmac_f32_e32 v2, v3, v3
	v_lshlrev_b32_e32 v3, 16, v23
	v_fmac_f32_e32 v2, v3, v3
	v_and_b32_e32 v3, 0xffff0000, v23
	v_fmac_f32_e32 v2, v3, v3
	s_waitcnt vmcnt(12)
; DI float bf_lo(unsigned w) { return __uint_as_float(w << 16); }
; DI float bf_hi(unsigned w) { return __uint_as_float(w & 0xffff0000u); }
; DI void gm_unit(const Ctx& cx, const bf16_t* __restrict__ PG, bf16_t* __restrict__ Ogm, const float* __restrict__ gvn, const float* __restrict__ ws, const float* __restrict__ bs, int unit, LAS unsigned char* lds) {
;     ...
;   { const int tt = tid >> 2, part = tid & 3; const bf16_t* vp = PG + (size_t)(tok0 + tt) * PGW + 4096; float ss = 0.f;
; #pragma unroll 8
;     for (int i = 0; i < 32; ++i) { const u32x4 w = *(const u32x4*)(vp + (i * 4 + part) * 8);
;       float g;
;       g = bf_lo(w.x); ss += g * g; g = bf_hi(w.x); ss += g * g; g = bf_lo(w.y); ss += g * g; g = bf_hi(w.y); ss += g * g;
;       g = bf_lo(w.z); ss += g * g; g = bf_hi(w.z); ss += g * g; g = bf_lo(w.w); ss += g * g; g = bf_hi(w.w); ss += g * g; }
;     ss += __shfl_xor(ss, 1); ss += __shfl_xor(ss, 2);
;     if (part == 0) rinv[tt] = rsqrtf(ss * (1.0f / 1024.0f) + EPS); }
	v_lshlrev_b32_e32 v3, 16, v24
	v_fmac_f32_e32 v2, v3, v3
	v_and_b32_e32 v3, 0xffff0000, v24
	v_fmac_f32_e32 v2, v3, v3
	v_lshlrev_b32_e32 v3, 16, v25
	v_fmac_f32_e32 v2, v3, v3
	v_and_b32_e32 v3, 0xffff0000, v25
	v_fmac_f32_e32 v2, v3, v3
	v_lshlrev_b32_e32 v3, 16, v26
	v_fmac_f32_e32 v2, v3, v3
	v_and_b32_e32 v3, 0xffff0000, v26
	v_fmac_f32_e32 v2, v3, v3
	v_lshlrev_b32_e32 v3, 16, v27
	v_fmac_f32_e32 v2, v3, v3
	v_and_b32_e32 v3, 0xffff0000, v27
	v_fmac_f32_e32 v2, v3, v3
	s_waitcnt vmcnt(11)
	v_lshlrev_b32_e32 v3, 16, v28
	v_fmac_f32_e32 v2, v3, v3
	v_and_b32_e32 v3, 0xffff0000, v28
	v_fmac_f32_e32 v2, v3, v3
	v_lshlrev_b32_e32 v3, 16, v29
	v_fmac_f32_e32 v2, v3, v3
	v_and_b32_e32 v3, 0xffff0000, v29
	v_fmac_f32_e32 v2, v3, v3
	v_lshlrev_b32_e32 v3, 16, v30
	v_fmac_f32_e32 v2, v3, v3
	v_and_b32_e32 v3, 0xffff0000, v30
	v_fmac_f32_e32 v2, v3, v3
	v_lshlrev_b32_e32 v3, 16, v31
	v_fmac_f32_e32 v2, v3, v3
	v_and_b32_e32 v3, 0xffff0000, v31
	v_fmac_f32_e32 v2, v3, v3
	s_waitcnt vmcnt(10)
	v_lshlrev_b32_e32 v3, 16, v146
	v_fmac_f32_e32 v2, v3, v3
	v_and_b32_e32 v3, 0xffff0000, v146
	v_fmac_f32_e32 v2, v3, v3
	v_lshlrev_b32_e32 v3, 16, v147
	v_fmac_f32_e32 v2, v3, v3
	v_and_b32_e32 v3, 0xffff0000, v147
	v_fmac_f32_e32 v2, v3, v3
	v_lshlrev_b32_e32 v3, 16, v148
	v_fmac_f32_e32 v2, v3, v3
	v_and_b32_e32 v3, 0xffff0000, v148
	v_fmac_f32_e32 v2, v3, v3
	v_lshlrev_b32_e32 v3, 16, v149
	v_fmac_f32_e32 v2, v3, v3
	v_and_b32_e32 v3, 0xffff0000, v149
	v_fmac_f32_e32 v2, v3, v3
	s_waitcnt vmcnt(9)
	v_lshlrev_b32_e32 v3, 16, v150
	v_fmac_f32_e32 v2, v3, v3
	v_and_b32_e32 v3, 0xffff0000, v150
	v_fmac_f32_e32 v2, v3, v3
	v_lshlrev_b32_e32 v3, 16, v151
	v_fmac_f32_e32 v2, v3, v3
	v_and_b32_e32 v3, 0xffff0000, v151
	v_fmac_f32_e32 v2, v3, v3
	v_lshlrev_b32_e32 v3, 16, v152
	v_fmac_f32_e32 v2, v3, v3
	v_and_b32_e32 v3, 0xffff0000, v152
	v_fmac_f32_e32 v2, v3, v3
	v_lshlrev_b32_e32 v3, 16, v153
	v_fmac_f32_e32 v2, v3, v3
	v_and_b32_e32 v3, 0xffff0000, v153
	v_fmac_f32_e32 v2, v3, v3
	s_waitcnt vmcnt(8)
	v_lshlrev_b32_e32 v3, 16, v154
	v_fmac_f32_e32 v2, v3, v3
	v_and_b32_e32 v3, 0xffff0000, v154
	v_fmac_f32_e32 v2, v3, v3
	v_lshlrev_b32_e32 v3, 16, v155
	v_fmac_f32_e32 v2, v3, v3
	v_and_b32_e32 v3, 0xffff0000, v155
	v_fmac_f32_e32 v2, v3, v3
	v_lshlrev_b32_e32 v3, 16, v156
	v_fmac_f32_e32 v2, v3, v3
	v_and_b32_e32 v3, 0xffff0000, v156
	v_fmac_f32_e32 v2, v3, v3
	v_lshlrev_b32_e32 v3, 16, v157
	v_fmac_f32_e32 v2, v3, v3
	v_and_b32_e32 v3, 0xffff0000, v157
	v_fmac_f32_e32 v2, v3, v3
	s_waitcnt vmcnt(7)
	v_lshlrev_b32_e32 v3, 16, v158
	v_fmac_f32_e32 v2, v3, v3
	v_and_b32_e32 v3, 0xffff0000, v158
	v_fmac_f32_e32 v2, v3, v3
	v_lshlrev_b32_e32 v3, 16, v159
	v_fmac_f32_e32 v2, v3, v3
	v_and_b32_e32 v3, 0xffff0000, v159
	v_fmac_f32_e32 v2, v3, v3
	v_lshlrev_b32_e32 v3, 16, v160
	v_fmac_f32_e32 v2, v3, v3
	v_and_b32_e32 v3, 0xffff0000, v160
	v_fmac_f32_e32 v2, v3, v3
	v_lshlrev_b32_e32 v3, 16, v161
	v_fmac_f32_e32 v2, v3, v3
	v_and_b32_e32 v3, 0xffff0000, v161
	v_fmac_f32_e32 v2, v3, v3
	s_waitcnt vmcnt(6)
	v_lshlrev_b32_e32 v3, 16, v162
	v_fmac_f32_e32 v2, v3, v3
	v_and_b32_e32 v3, 0xffff0000, v162
	v_fmac_f32_e32 v2, v3, v3
	v_lshlrev_b32_e32 v3, 16, v163
	v_fmac_f32_e32 v2, v3, v3
	v_and_b32_e32 v3, 0xffff0000, v163
	v_fmac_f32_e32 v2, v3, v3
	v_lshlrev_b32_e32 v3, 16, v164
	v_fmac_f32_e32 v2, v3, v3
	v_and_b32_e32 v3, 0xffff0000, v164
	v_fmac_f32_e32 v2, v3, v3
	v_lshlrev_b32_e32 v3, 16, v165
	v_fmac_f32_e32 v2, v3, v3
	v_and_b32_e32 v3, 0xffff0000, v165
	v_fmac_f32_e32 v2, v3, v3
	s_waitcnt vmcnt(5)
	v_lshlrev_b32_e32 v3, 16, v180
	v_fmac_f32_e32 v2, v3, v3
	v_and_b32_e32 v3, 0xffff0000, v180
	v_fmac_f32_e32 v2, v3, v3
	v_lshlrev_b32_e32 v3, 16, v181
	v_fmac_f32_e32 v2, v3, v3
	v_and_b32_e32 v3, 0xffff0000, v181
	v_fmac_f32_e32 v2, v3, v3
	v_lshlrev_b32_e32 v3, 16, v182
	v_fmac_f32_e32 v2, v3, v3
	v_and_b32_e32 v3, 0xffff0000, v182
	v_fmac_f32_e32 v2, v3, v3
	v_lshlrev_b32_e32 v3, 16, v183
	v_fmac_f32_e32 v2, v3, v3
	v_and_b32_e32 v3, 0xffff0000, v183
	v_fmac_f32_e32 v2, v3, v3
	s_waitcnt vmcnt(4)
	v_lshlrev_b32_e32 v3, 16, v184
	v_fmac_f32_e32 v2, v3, v3
	v_and_b32_e32 v3, 0xffff0000, v184
	v_fmac_f32_e32 v2, v3, v3
	v_lshlrev_b32_e32 v3, 16, v185
	v_fmac_f32_e32 v2, v3, v3
	v_and_b32_e32 v3, 0xffff0000, v185
	v_fmac_f32_e32 v2, v3, v3
	v_lshlrev_b32_e32 v3, 16, v186
	v_fmac_f32_e32 v2, v3, v3
	v_and_b32_e32 v3, 0xffff0000, v186
	v_fmac_f32_e32 v2, v3, v3
	v_lshlrev_b32_e32 v3, 16, v187
	v_fmac_f32_e32 v2, v3, v3
	v_and_b32_e32 v3, 0xffff0000, v187
	v_fmac_f32_e32 v2, v3, v3
	s_waitcnt vmcnt(3)
	v_lshlrev_b32_e32 v3, 16, v188
	v_fmac_f32_e32 v2, v3, v3
	v_and_b32_e32 v3, 0xffff0000, v188
	v_fmac_f32_e32 v2, v3, v3
	v_lshlrev_b32_e32 v3, 16, v189
	v_fmac_f32_e32 v2, v3, v3
	v_and_b32_e32 v3, 0xffff0000, v189
	v_fmac_f32_e32 v2, v3, v3
	v_lshlrev_b32_e32 v3, 16, v190
	v_fmac_f32_e32 v2, v3, v3
	v_and_b32_e32 v3, 0xffff0000, v190
	v_fmac_f32_e32 v2, v3, v3
	v_lshlrev_b32_e32 v3, 16, v191
	v_fmac_f32_e32 v2, v3, v3
	v_and_b32_e32 v3, 0xffff0000, v191
	v_fmac_f32_e32 v2, v3, v3
	s_waitcnt vmcnt(2)
	v_lshlrev_b32_e32 v3, 16, v192
	v_fmac_f32_e32 v2, v3, v3
	v_and_b32_e32 v3, 0xffff0000, v192
	v_fmac_f32_e32 v2, v3, v3
	v_lshlrev_b32_e32 v3, 16, v193
	v_fmac_f32_e32 v2, v3, v3
	v_and_b32_e32 v3, 0xffff0000, v193
	v_fmac_f32_e32 v2, v3, v3
	v_lshlrev_b32_e32 v3, 16, v194
	v_fmac_f32_e32 v2, v3, v3
	v_and_b32_e32 v3, 0xffff0000, v194
	v_fmac_f32_e32 v2, v3, v3
	v_lshlrev_b32_e32 v3, 16, v195
	v_fmac_f32_e32 v2, v3, v3
	v_and_b32_e32 v3, 0xffff0000, v195
	v_fmac_f32_e32 v2, v3, v3
	s_waitcnt vmcnt(1)
	v_lshlrev_b32_e32 v3, 16, v196
	v_fmac_f32_e32 v2, v3, v3
	v_and_b32_e32 v3, 0xffff0000, v196
	v_fmac_f32_e32 v2, v3, v3
	v_lshlrev_b32_e32 v3, 16, v197
	v_fmac_f32_e32 v2, v3, v3
	v_and_b32_e32 v3, 0xffff0000, v197
	v_fmac_f32_e32 v2, v3, v3
	v_lshlrev_b32_e32 v3, 16, v198
	v_fmac_f32_e32 v2, v3, v3
	v_and_b32_e32 v3, 0xffff0000, v198
	v_fmac_f32_e32 v2, v3, v3
	v_lshlrev_b32_e32 v3, 16, v199
	v_fmac_f32_e32 v2, v3, v3
	v_and_b32_e32 v3, 0xffff0000, v199
	v_fmac_f32_e32 v2, v3, v3
	s_waitcnt vmcnt(0)
	v_lshlrev_b32_e32 v3, 16, v200
	v_fmac_f32_e32 v2, v3, v3
	v_and_b32_e32 v3, 0xffff0000, v200
	v_fmac_f32_e32 v2, v3, v3
	v_lshlrev_b32_e32 v3, 16, v201
	v_fmac_f32_e32 v2, v3, v3
	v_and_b32_e32 v3, 0xffff0000, v201
	v_fmac_f32_e32 v2, v3, v3
	v_lshlrev_b32_e32 v3, 16, v202
	v_fmac_f32_e32 v2, v3, v3
	v_and_b32_e32 v3, 0xffff0000, v202
	v_fmac_f32_e32 v2, v3, v3
	v_lshlrev_b32_e32 v3, 16, v203
	v_fmac_f32_e32 v2, v3, v3
	v_and_b32_e32 v3, 0xffff0000, v203
	v_fmac_f32_e32 v2, v3, v3
	ds_bpermute_b32 v0, v89, v2
	v_readfirstlane_b32 s25, v242
	s_waitcnt lgkmcnt(0)
	v_add_f32_e32 v0, v2, v0
	ds_bpermute_b32 v1, v136, v0
	s_and_saveexec_b64 s[22:23], s[34:35]
	s_cbranch_execz .LBB0_915
; DI void gm_unit(const Ctx& cx, const bf16_t* __restrict__ PG, bf16_t* __restrict__ Ogm, const float* __restrict__ gvn, const float* __restrict__ ws, const float* __restrict__ bs, int unit, LAS unsigned char* lds) {
;     ...
;     ss += __shfl_xor(ss, 1); ss += __shfl_xor(ss, 2);
;     if (part == 0) rinv[tt] = rsqrtf(ss * (1.0f / 1024.0f) + EPS); }
	s_waitcnt lgkmcnt(0)
	v_add_f32_e32 v0, v0, v1
	v_fmamk_f32 v0, v0, 0x3a800000, v235
	v_mul_f32_e32 v1, 0x4b800000, v0
	v_cmp_gt_f32_e32 vcc, s95, v0
	s_nop 1
	v_cndmask_b32_e32 v0, v0, v1, vcc
	v_rsq_f32_e32 v0, v0
	s_nop 0
	v_mul_f32_e32 v1, 0x45800000, v0
	v_cndmask_b32_e32 v0, v0, v1, vcc
	ds_write_b32 v137, v0 offset:49152
